# code placement: the ten GEMM K-loop heads aligned to 64 bytes (p2align 6), otherwise identical to the one-way-barrier version
# baseline (speedup 1.0000x reference)
; template <class Epi, bool ALIGN_EPI>
; __device__ __forceinline__ void gemm_phase(LAS unsigned char* lds, const Gemm g, const StaticOrder& S, const Epi& E) {
;     ...
;         const bool has_next = S.next(ui + 1, nxt);
;         const char* nA = has_next ? (const char*)g.A + (size_t)nxt.pm * tstepA : cA; const char* nB = has_next ? (const char*)g.Bt + (size_t)nxt.pn * tstepB : cB;
;     ...
; #pragma unroll
;         for (int a = 0; a < 2; ++a)
; #pragma unroll
;             for (int b = 0; b < 2; ++b)
; #pragma unroll
;                 for (int m = 0; m < 4; ++m)
; #pragma unroll
;                     for (int n = 0; n < 2; ++n) acc[a][b][m][n] = (f32x4){0.f, 0.f, 0.f, 0.f};
.LBB0_101:
	s_ashr_i32 s13, s12, 31
	s_lshl_b64 s[8:9], s[12:13], 19
	v_readlane_b32 s4, v254, 45
	v_readlane_b32 s5, v254, 46
	s_add_u32 s30, s4, s8
	s_addc_u32 s31, s5, s9
	s_and_b64 s[8:9], s[28:29], exec
	s_cselect_b32 s4, s31, s3
	s_cselect_b32 s10, s30, s2
	s_ashr_i32 s27, s26, 31
	s_lshl_b64 s[8:9], s[26:27], 19
	s_add_u32 s34, s38, s8
	s_addc_u32 s35, s39, s9
	s_and_b64 s[8:9], s[28:29], exec
	s_cselect_b32 s11, s35, s7
	s_cselect_b32 s13, s34, s6
	s_add_u32 s2, s2, 0x40080
	s_addc_u32 s3, s3, 0
	s_add_u32 s27, s6, 0x100
	v_mov_b32_e32 v2, 0
	s_addc_u32 s36, s7, 0
	s_mov_b32 s37, -2
	s_waitcnt lgkmcnt(0)
	v_mov_b32_e32 v3, v2
	v_mov_b32_e32 v4, v2
	v_mov_b32_e32 v5, v2
	v_mov_b32_e32 v6, v2
	v_mov_b32_e32 v7, v2
	v_mov_b32_e32 v8, v2
	v_mov_b32_e32 v9, v2
	v_mov_b32_e32 v18, v2
	v_mov_b32_e32 v19, v2
	v_mov_b32_e32 v20, v2
	v_mov_b32_e32 v21, v2
	v_mov_b32_e32 v22, v2
	v_mov_b32_e32 v23, v2
	v_mov_b32_e32 v24, v2
	v_mov_b32_e32 v25, v2
	v_mov_b32_e32 v34, v2
	v_mov_b32_e32 v35, v2
	v_mov_b32_e32 v36, v2
	v_mov_b32_e32 v37, v2
	v_mov_b32_e32 v38, v2
	v_mov_b32_e32 v39, v2
	v_mov_b32_e32 v40, v2
	v_mov_b32_e32 v41, v2
	v_mov_b32_e32 v50, v2
	v_mov_b32_e32 v51, v2
	v_mov_b32_e32 v52, v2
	v_mov_b32_e32 v53, v2
	v_mov_b32_e32 v54, v2
	v_mov_b32_e32 v55, v2
	v_mov_b32_e32 v56, v2
	v_mov_b32_e32 v57, v2
	v_mov_b32_e32 v10, v2
	v_mov_b32_e32 v11, v2
	v_mov_b32_e32 v12, v2
	v_mov_b32_e32 v13, v2
	v_mov_b32_e32 v14, v2
	v_mov_b32_e32 v15, v2
	v_mov_b32_e32 v16, v2
	v_mov_b32_e32 v17, v2
	v_mov_b32_e32 v26, v2
	v_mov_b32_e32 v27, v2
	v_mov_b32_e32 v28, v2
	v_mov_b32_e32 v29, v2
	v_mov_b32_e32 v30, v2
	v_mov_b32_e32 v31, v2
	v_mov_b32_e32 v32, v2
	v_mov_b32_e32 v33, v2
	v_mov_b32_e32 v42, v2
	v_mov_b32_e32 v43, v2
	v_mov_b32_e32 v44, v2
	v_mov_b32_e32 v45, v2
	v_mov_b32_e32 v46, v2
	v_mov_b32_e32 v47, v2
	v_mov_b32_e32 v48, v2
	v_mov_b32_e32 v49, v2
	v_mov_b32_e32 v58, v2
	v_mov_b32_e32 v59, v2
	v_mov_b32_e32 v60, v2
	v_mov_b32_e32 v61, v2
	v_mov_b32_e32 v62, v2
	v_mov_b32_e32 v63, v2
	v_mov_b32_e32 v64, v2
	v_mov_b32_e32 v65, v2
	v_mov_b32_e32 v66, v2
	v_mov_b32_e32 v67, v2
	v_mov_b32_e32 v68, v2
	v_mov_b32_e32 v69, v2
	v_mov_b32_e32 v70, v2
	v_mov_b32_e32 v71, v2
	v_mov_b32_e32 v72, v2
	v_mov_b32_e32 v73, v2
	v_mov_b32_e32 v82, v2
	v_mov_b32_e32 v83, v2
	v_mov_b32_e32 v84, v2
	v_mov_b32_e32 v85, v2
	v_mov_b32_e32 v86, v2
	v_mov_b32_e32 v87, v2
	v_mov_b32_e32 v88, v2
	v_mov_b32_e32 v89, v2
	v_mov_b32_e32 v98, v2
	v_mov_b32_e32 v99, v2
	v_mov_b32_e32 v100, v2
	v_mov_b32_e32 v101, v2
	v_mov_b32_e32 v102, v2
	v_mov_b32_e32 v103, v2
	v_mov_b32_e32 v104, v2
	v_mov_b32_e32 v105, v2
	v_mov_b32_e32 v114, v2
	v_mov_b32_e32 v115, v2
	v_mov_b32_e32 v116, v2
	v_mov_b32_e32 v117, v2
	v_mov_b32_e32 v118, v2
	v_mov_b32_e32 v119, v2
	v_mov_b32_e32 v120, v2
	v_mov_b32_e32 v121, v2
	v_mov_b32_e32 v74, v2
	v_mov_b32_e32 v75, v2
	v_mov_b32_e32 v76, v2
	v_mov_b32_e32 v77, v2
	v_mov_b32_e32 v78, v2
	v_mov_b32_e32 v79, v2
	v_mov_b32_e32 v80, v2
	v_mov_b32_e32 v81, v2
	v_mov_b32_e32 v90, v2
	v_mov_b32_e32 v91, v2
	v_mov_b32_e32 v92, v2
	v_mov_b32_e32 v93, v2
	v_mov_b32_e32 v94, v2
	v_mov_b32_e32 v95, v2
	v_mov_b32_e32 v96, v2
	v_mov_b32_e32 v97, v2
	v_mov_b32_e32 v106, v2
	v_mov_b32_e32 v107, v2
	v_mov_b32_e32 v108, v2
	v_mov_b32_e32 v109, v2
	v_mov_b32_e32 v110, v2
	v_mov_b32_e32 v111, v2
	v_mov_b32_e32 v112, v2
	v_mov_b32_e32 v113, v2
	v_mov_b32_e32 v126, v2
	v_mov_b32_e32 v127, v2
	v_mov_b32_e32 v128, v2
	v_mov_b32_e32 v129, v2
	v_mov_b32_e32 v122, v2
	v_mov_b32_e32 v123, v2
	v_mov_b32_e32 v124, v2
	v_mov_b32_e32 v125, v2
	.p2align 6

; template <class Epi, bool ALIGN_EPI>
; __device__ __forceinline__ void gemm_phase(LAS unsigned char* lds, const Gemm g, const StaticOrder& S, const Epi& E) {
;     ...
;         for (int t = 0; t < nt; t += 2) {
;             const bool last = (t == nt - 2);
;             const char* a1 = cA + (size_t)(t + 1) * kstep;
;             const char* a2 = last ? nA : cA + (size_t)(t + 2) * kstep; const char* b2 = last ? nB : cB + (size_t)(t + 2) * kstep;
;             const char* a3 = a2 + kstep; const char* b3 = b2 + kstep;
;     ...
; #pragma unroll
;         for (int a = 0; a < 2; ++a)
; #pragma unroll
;             for (int b = 0; b < 2; ++b)
; #pragma unroll
;                 for (int m = 0; m < 4; ++m)
; #pragma unroll
;                     for (int n = 0; n < 2; ++n) acc[a][b][m][n] = (f32x4){0.f, 0.f, 0.f, 0.f};
.LBB0_215:
	s_add_u32 s41, s12, 0x100
	v_mov_b32_e32 v2, 0
	s_addc_u32 s42, s13, 0
	s_mov_b32 s43, -2
	s_waitcnt lgkmcnt(0)
	v_mov_b32_e32 v3, v2
	v_mov_b32_e32 v4, v2
	v_mov_b32_e32 v5, v2
	v_mov_b32_e32 v6, v2
	v_mov_b32_e32 v7, v2
	v_mov_b32_e32 v8, v2
	v_mov_b32_e32 v9, v2
	v_mov_b32_e32 v18, v2
	v_mov_b32_e32 v19, v2
	v_mov_b32_e32 v20, v2
	v_mov_b32_e32 v21, v2
	v_mov_b32_e32 v22, v2
	v_mov_b32_e32 v23, v2
	v_mov_b32_e32 v24, v2
	v_mov_b32_e32 v25, v2
	v_mov_b32_e32 v34, v2
	v_mov_b32_e32 v35, v2
	v_mov_b32_e32 v36, v2
	v_mov_b32_e32 v37, v2
	v_mov_b32_e32 v38, v2
	v_mov_b32_e32 v39, v2
	v_mov_b32_e32 v40, v2
	v_mov_b32_e32 v41, v2
	v_mov_b32_e32 v50, v2
	v_mov_b32_e32 v51, v2
	v_mov_b32_e32 v52, v2
	v_mov_b32_e32 v53, v2
	v_mov_b32_e32 v54, v2
	v_mov_b32_e32 v55, v2
	v_mov_b32_e32 v56, v2
	v_mov_b32_e32 v57, v2
	v_mov_b32_e32 v10, v2
	v_mov_b32_e32 v11, v2
	v_mov_b32_e32 v12, v2
	v_mov_b32_e32 v13, v2
	v_mov_b32_e32 v14, v2
	v_mov_b32_e32 v15, v2
	v_mov_b32_e32 v16, v2
	v_mov_b32_e32 v17, v2
	v_mov_b32_e32 v26, v2
	v_mov_b32_e32 v27, v2
	v_mov_b32_e32 v28, v2
	v_mov_b32_e32 v29, v2
	v_mov_b32_e32 v30, v2
	v_mov_b32_e32 v31, v2
	v_mov_b32_e32 v32, v2
	v_mov_b32_e32 v33, v2
	v_mov_b32_e32 v42, v2
	v_mov_b32_e32 v43, v2
	v_mov_b32_e32 v44, v2
	v_mov_b32_e32 v45, v2
	v_mov_b32_e32 v46, v2
	v_mov_b32_e32 v47, v2
	v_mov_b32_e32 v48, v2
	v_mov_b32_e32 v49, v2
	v_mov_b32_e32 v58, v2
	v_mov_b32_e32 v59, v2
	v_mov_b32_e32 v60, v2
	v_mov_b32_e32 v61, v2
	v_mov_b32_e32 v62, v2
	v_mov_b32_e32 v63, v2
	v_mov_b32_e32 v64, v2
	v_mov_b32_e32 v65, v2
	v_mov_b32_e32 v66, v2
	v_mov_b32_e32 v67, v2
	v_mov_b32_e32 v68, v2
	v_mov_b32_e32 v69, v2
	v_mov_b32_e32 v70, v2
	v_mov_b32_e32 v71, v2
	v_mov_b32_e32 v72, v2
	v_mov_b32_e32 v73, v2
	v_mov_b32_e32 v82, v2
	v_mov_b32_e32 v83, v2
	v_mov_b32_e32 v84, v2
	v_mov_b32_e32 v85, v2
	v_mov_b32_e32 v86, v2
	v_mov_b32_e32 v87, v2
	v_mov_b32_e32 v88, v2
	v_mov_b32_e32 v89, v2
	v_mov_b32_e32 v98, v2
	v_mov_b32_e32 v99, v2
	v_mov_b32_e32 v100, v2
	v_mov_b32_e32 v101, v2
	v_mov_b32_e32 v102, v2
	v_mov_b32_e32 v103, v2
	v_mov_b32_e32 v104, v2
	v_mov_b32_e32 v105, v2
	v_mov_b32_e32 v114, v2
	v_mov_b32_e32 v115, v2
	v_mov_b32_e32 v116, v2
	v_mov_b32_e32 v117, v2
	v_mov_b32_e32 v118, v2
	v_mov_b32_e32 v119, v2
	v_mov_b32_e32 v120, v2
	v_mov_b32_e32 v121, v2
	v_mov_b32_e32 v74, v2
	v_mov_b32_e32 v75, v2
	v_mov_b32_e32 v76, v2
	v_mov_b32_e32 v77, v2
	v_mov_b32_e32 v78, v2
	v_mov_b32_e32 v79, v2
	v_mov_b32_e32 v80, v2
	v_mov_b32_e32 v81, v2
	v_mov_b32_e32 v90, v2
	v_mov_b32_e32 v91, v2
	v_mov_b32_e32 v92, v2
	v_mov_b32_e32 v93, v2
	v_mov_b32_e32 v94, v2
	v_mov_b32_e32 v95, v2
	v_mov_b32_e32 v96, v2
	v_mov_b32_e32 v97, v2
	v_mov_b32_e32 v106, v2
	v_mov_b32_e32 v107, v2
	v_mov_b32_e32 v108, v2
	v_mov_b32_e32 v109, v2
	v_mov_b32_e32 v110, v2
	v_mov_b32_e32 v111, v2
	v_mov_b32_e32 v112, v2
	v_mov_b32_e32 v113, v2
	v_mov_b32_e32 v122, v2
	v_mov_b32_e32 v123, v2
	v_mov_b32_e32 v124, v2
	v_mov_b32_e32 v125, v2
	v_mov_b32_e32 v126, v2
	v_mov_b32_e32 v127, v2
	v_mov_b32_e32 v128, v2
	v_mov_b32_e32 v129, v2
	.p2align 6

; template <class Epi, bool ALIGN_EPI>
; __device__ __forceinline__ void gemm_phase(LAS unsigned char* lds, const Gemm g, const StaticOrder& S, const Epi& E) {
;     ...
;         const bool has_next = S.next(ui + 1, nxt);
;         const char* nA = has_next ? (const char*)g.A + (size_t)nxt.pm * tstepA : cA; const char* nB = has_next ? (const char*)g.Bt + (size_t)nxt.pn * tstepB : cB;
;     ...
; #pragma unroll
;         for (int a = 0; a < 2; ++a)
; #pragma unroll
;             for (int b = 0; b < 2; ++b)
; #pragma unroll
;                 for (int m = 0; m < 4; ++m)
; #pragma unroll
;                     for (int n = 0; n < 2; ++n) acc[a][b][m][n] = (f32x4){0.f, 0.f, 0.f, 0.f};
.LBB0_303:
	s_ashr_i32 s1, s0, 31
	s_lshl_b64 s[14:15], s[0:1], 19
	v_readlane_b32 s16, v254, 45
	v_readlane_b32 s17, v254, 46
	s_add_u32 s14, s16, s14
	s_addc_u32 s15, s17, s15
	s_and_b64 s[16:17], s[12:13], exec
	s_cselect_b32 s1, s15, s7
	s_cselect_b32 s36, s14, s6
	s_ashr_i32 s11, s10, 31
	s_lshl_b64 s[16:17], s[10:11], 19
	s_add_u32 s16, s22, s16
	s_addc_u32 s17, s23, s17
	s_and_b64 s[20:21], s[12:13], exec
	s_cselect_b32 s11, s17, s19
	s_cselect_b32 s37, s16, s18
	s_add_u32 s6, s6, 0x40080
	s_addc_u32 s7, s7, 0
	s_add_u32 s38, s18, 0x100
	v_mov_b32_e32 v2, 0
	s_addc_u32 s39, s19, 0
	s_mov_b32 s40, -2
	v_mov_b32_e32 v3, v2
	v_mov_b32_e32 v4, v2
	v_mov_b32_e32 v5, v2
	v_mov_b32_e32 v10, v2
	v_mov_b32_e32 v11, v2
	v_mov_b32_e32 v12, v2
	v_mov_b32_e32 v13, v2
	v_mov_b32_e32 v18, v2
	v_mov_b32_e32 v19, v2
	v_mov_b32_e32 v20, v2
	v_mov_b32_e32 v21, v2
	v_mov_b32_e32 v26, v2
	v_mov_b32_e32 v27, v2
	v_mov_b32_e32 v28, v2
	v_mov_b32_e32 v29, v2
	v_mov_b32_e32 v34, v2
	v_mov_b32_e32 v35, v2
	v_mov_b32_e32 v36, v2
	v_mov_b32_e32 v37, v2
	v_mov_b32_e32 v42, v2
	v_mov_b32_e32 v43, v2
	v_mov_b32_e32 v44, v2
	v_mov_b32_e32 v45, v2
	v_mov_b32_e32 v50, v2
	v_mov_b32_e32 v51, v2
	v_mov_b32_e32 v52, v2
	v_mov_b32_e32 v53, v2
	v_mov_b32_e32 v58, v2
	v_mov_b32_e32 v59, v2
	v_mov_b32_e32 v60, v2
	v_mov_b32_e32 v61, v2
	v_mov_b32_e32 v6, v2
	v_mov_b32_e32 v7, v2
	v_mov_b32_e32 v8, v2
	v_mov_b32_e32 v9, v2
	v_mov_b32_e32 v14, v2
	v_mov_b32_e32 v15, v2
	v_mov_b32_e32 v16, v2
	v_mov_b32_e32 v17, v2
	v_mov_b32_e32 v22, v2
	v_mov_b32_e32 v23, v2
	v_mov_b32_e32 v24, v2
	v_mov_b32_e32 v25, v2
	v_mov_b32_e32 v30, v2
	v_mov_b32_e32 v31, v2
	v_mov_b32_e32 v32, v2
	v_mov_b32_e32 v33, v2
	v_mov_b32_e32 v38, v2
	v_mov_b32_e32 v39, v2
	v_mov_b32_e32 v40, v2
	v_mov_b32_e32 v41, v2
	v_mov_b32_e32 v46, v2
	v_mov_b32_e32 v47, v2
	v_mov_b32_e32 v48, v2
	v_mov_b32_e32 v49, v2
	v_mov_b32_e32 v54, v2
	v_mov_b32_e32 v55, v2
	v_mov_b32_e32 v56, v2
	v_mov_b32_e32 v57, v2
	v_mov_b32_e32 v62, v2
	v_mov_b32_e32 v63, v2
	v_mov_b32_e32 v64, v2
	v_mov_b32_e32 v65, v2
	v_mov_b32_e32 v66, v2
	v_mov_b32_e32 v67, v2
	v_mov_b32_e32 v68, v2
	v_mov_b32_e32 v69, v2
	v_mov_b32_e32 v74, v2
	v_mov_b32_e32 v75, v2
	v_mov_b32_e32 v76, v2
	v_mov_b32_e32 v77, v2
	v_mov_b32_e32 v82, v2
	v_mov_b32_e32 v83, v2
	v_mov_b32_e32 v84, v2
	v_mov_b32_e32 v85, v2
	v_mov_b32_e32 v90, v2
	v_mov_b32_e32 v91, v2
	v_mov_b32_e32 v92, v2
	v_mov_b32_e32 v93, v2
	v_mov_b32_e32 v98, v2
	v_mov_b32_e32 v99, v2
	v_mov_b32_e32 v100, v2
	v_mov_b32_e32 v101, v2
	v_mov_b32_e32 v106, v2
	v_mov_b32_e32 v107, v2
	v_mov_b32_e32 v108, v2
	v_mov_b32_e32 v109, v2
	v_mov_b32_e32 v114, v2
	v_mov_b32_e32 v115, v2
	v_mov_b32_e32 v116, v2
	v_mov_b32_e32 v117, v2
	v_mov_b32_e32 v122, v2
	v_mov_b32_e32 v123, v2
	v_mov_b32_e32 v124, v2
	v_mov_b32_e32 v125, v2
	v_mov_b32_e32 v70, v2
	v_mov_b32_e32 v71, v2
	v_mov_b32_e32 v72, v2
	v_mov_b32_e32 v73, v2
	v_mov_b32_e32 v78, v2
	v_mov_b32_e32 v79, v2
	v_mov_b32_e32 v80, v2
	v_mov_b32_e32 v81, v2
	v_mov_b32_e32 v86, v2
	v_mov_b32_e32 v87, v2
	v_mov_b32_e32 v88, v2
	v_mov_b32_e32 v89, v2
	v_mov_b32_e32 v94, v2
	v_mov_b32_e32 v95, v2
	v_mov_b32_e32 v96, v2
	v_mov_b32_e32 v97, v2
	v_mov_b32_e32 v102, v2
	v_mov_b32_e32 v103, v2
	v_mov_b32_e32 v104, v2
	v_mov_b32_e32 v105, v2
	v_mov_b32_e32 v110, v2
	v_mov_b32_e32 v111, v2
	v_mov_b32_e32 v112, v2
	v_mov_b32_e32 v113, v2
	v_mov_b32_e32 v118, v2
	v_mov_b32_e32 v119, v2
	v_mov_b32_e32 v120, v2
	v_mov_b32_e32 v121, v2
	v_mov_b32_e32 v126, v2
	v_mov_b32_e32 v127, v2
	v_mov_b32_e32 v128, v2
	v_mov_b32_e32 v129, v2
	.p2align 6

; template <class Epi, bool ALIGN_EPI>
; __device__ __forceinline__ void gemm_phase(LAS unsigned char* lds, const Gemm g, const StaticOrder& S, const Epi& E) {
;     ...
;         const bool has_next = S.next(ui + 1, nxt);
;         const char* nA = has_next ? (const char*)g.A + (size_t)nxt.pm * tstepA : cA; const char* nB = has_next ? (const char*)g.Bt + (size_t)nxt.pn * tstepB : cB;
;         for (int t = 0; t < nt; t += 2) {
;     ...
; #pragma unroll
;         for (int a = 0; a < 2; ++a)
; #pragma unroll
;             for (int b = 0; b < 2; ++b)
; #pragma unroll
;                 for (int m = 0; m < 4; ++m)
; #pragma unroll
;                     for (int n = 0; n < 2; ++n) acc[a][b][m][n] = (f32x4){0.f, 0.f, 0.f, 0.f};
.LBB0_337:
	s_ashr_i32 s15, s14, 31
	s_lshl_b64 s[18:19], s[14:15], 19
	s_add_u32 s18, s26, s18
	s_addc_u32 s19, s27, s19
	s_and_b64 s[22:23], s[22:23], exec
	s_cselect_b32 s15, s19, s11
	s_cselect_b32 s21, s18, s10
	s_add_u32 s39, s10, 0x100
	v_mov_b32_e32 v2, 0
	s_addc_u32 s40, s11, 0
	s_mov_b32 s41, -2
	s_waitcnt lgkmcnt(0)
	v_mov_b32_e32 v3, v2
	v_mov_b32_e32 v4, v2
	v_mov_b32_e32 v5, v2
	v_mov_b32_e32 v6, v2
	v_mov_b32_e32 v7, v2
	v_mov_b32_e32 v8, v2
	v_mov_b32_e32 v9, v2
	v_mov_b32_e32 v18, v2
	v_mov_b32_e32 v19, v2
	v_mov_b32_e32 v20, v2
	v_mov_b32_e32 v21, v2
	v_mov_b32_e32 v22, v2
	v_mov_b32_e32 v23, v2
	v_mov_b32_e32 v24, v2
	v_mov_b32_e32 v25, v2
	v_mov_b32_e32 v34, v2
	v_mov_b32_e32 v35, v2
	v_mov_b32_e32 v36, v2
	v_mov_b32_e32 v37, v2
	v_mov_b32_e32 v38, v2
	v_mov_b32_e32 v39, v2
	v_mov_b32_e32 v40, v2
	v_mov_b32_e32 v41, v2
	v_mov_b32_e32 v50, v2
	v_mov_b32_e32 v51, v2
	v_mov_b32_e32 v52, v2
	v_mov_b32_e32 v53, v2
	v_mov_b32_e32 v54, v2
	v_mov_b32_e32 v55, v2
	v_mov_b32_e32 v56, v2
	v_mov_b32_e32 v57, v2
	v_mov_b32_e32 v10, v2
	v_mov_b32_e32 v11, v2
	v_mov_b32_e32 v12, v2
	v_mov_b32_e32 v13, v2
	v_mov_b32_e32 v14, v2
	v_mov_b32_e32 v15, v2
	v_mov_b32_e32 v16, v2
	v_mov_b32_e32 v17, v2
	v_mov_b32_e32 v26, v2
	v_mov_b32_e32 v27, v2
	v_mov_b32_e32 v28, v2
	v_mov_b32_e32 v29, v2
	v_mov_b32_e32 v30, v2
	v_mov_b32_e32 v31, v2
	v_mov_b32_e32 v32, v2
	v_mov_b32_e32 v33, v2
	v_mov_b32_e32 v42, v2
	v_mov_b32_e32 v43, v2
	v_mov_b32_e32 v44, v2
	v_mov_b32_e32 v45, v2
	v_mov_b32_e32 v46, v2
	v_mov_b32_e32 v47, v2
	v_mov_b32_e32 v48, v2
	v_mov_b32_e32 v49, v2
	v_mov_b32_e32 v58, v2
	v_mov_b32_e32 v59, v2
	v_mov_b32_e32 v60, v2
	v_mov_b32_e32 v61, v2
	v_mov_b32_e32 v62, v2
	v_mov_b32_e32 v63, v2
	v_mov_b32_e32 v64, v2
	v_mov_b32_e32 v65, v2
	v_mov_b32_e32 v66, v2
	v_mov_b32_e32 v67, v2
	v_mov_b32_e32 v68, v2
	v_mov_b32_e32 v69, v2
	v_mov_b32_e32 v70, v2
	v_mov_b32_e32 v71, v2
	v_mov_b32_e32 v72, v2
	v_mov_b32_e32 v73, v2
	v_mov_b32_e32 v82, v2
	v_mov_b32_e32 v83, v2
	v_mov_b32_e32 v84, v2
	v_mov_b32_e32 v85, v2
	v_mov_b32_e32 v86, v2
	v_mov_b32_e32 v87, v2
	v_mov_b32_e32 v88, v2
	v_mov_b32_e32 v89, v2
	v_mov_b32_e32 v98, v2
	v_mov_b32_e32 v99, v2
	v_mov_b32_e32 v100, v2
	v_mov_b32_e32 v101, v2
	v_mov_b32_e32 v102, v2
	v_mov_b32_e32 v103, v2
	v_mov_b32_e32 v104, v2
	v_mov_b32_e32 v105, v2
	v_mov_b32_e32 v114, v2
	v_mov_b32_e32 v115, v2
	v_mov_b32_e32 v116, v2
	v_mov_b32_e32 v117, v2
	v_mov_b32_e32 v118, v2
	v_mov_b32_e32 v119, v2
	v_mov_b32_e32 v120, v2
	v_mov_b32_e32 v121, v2
	v_mov_b32_e32 v74, v2
	v_mov_b32_e32 v75, v2
	v_mov_b32_e32 v76, v2
	v_mov_b32_e32 v77, v2
	v_mov_b32_e32 v78, v2
	v_mov_b32_e32 v79, v2
	v_mov_b32_e32 v80, v2
	v_mov_b32_e32 v81, v2
	v_mov_b32_e32 v90, v2
	v_mov_b32_e32 v91, v2
	v_mov_b32_e32 v92, v2
	v_mov_b32_e32 v93, v2
	v_mov_b32_e32 v94, v2
	v_mov_b32_e32 v95, v2
	v_mov_b32_e32 v96, v2
	v_mov_b32_e32 v97, v2
	v_mov_b32_e32 v106, v2
	v_mov_b32_e32 v107, v2
	v_mov_b32_e32 v108, v2
	v_mov_b32_e32 v109, v2
	v_mov_b32_e32 v110, v2
	v_mov_b32_e32 v111, v2
	v_mov_b32_e32 v112, v2
	v_mov_b32_e32 v113, v2
	v_mov_b32_e32 v122, v2
	v_mov_b32_e32 v123, v2
	v_mov_b32_e32 v124, v2
	v_mov_b32_e32 v125, v2
	v_mov_b32_e32 v126, v2
	v_mov_b32_e32 v127, v2
	v_mov_b32_e32 v128, v2
	v_mov_b32_e32 v129, v2
	.p2align 6

; template <class Epi, bool ALIGN_EPI>
; __device__ __forceinline__ void gemm_phase(LAS unsigned char* lds, const Gemm g, const StaticOrder& S, const Epi& E) {
;     ...
;         const bool has_next = S.next(ui + 1, nxt);
;         const char* nA = has_next ? (const char*)g.A + (size_t)nxt.pm * tstepA : cA; const char* nB = has_next ? (const char*)g.Bt + (size_t)nxt.pn * tstepB : cB;
;         for (int t = 0; t < nt; t += 2) {
;     ...
; #pragma unroll
;         for (int a = 0; a < 2; ++a)
; #pragma unroll
;             for (int b = 0; b < 2; ++b)
; #pragma unroll
;                 for (int m = 0; m < 4; ++m)
; #pragma unroll
;                     for (int n = 0; n < 2; ++n) acc[a][b][m][n] = (f32x4){0.f, 0.f, 0.f, 0.f};
.LBB0_413:
	s_ashr_i32 s15, s14, 31
	s_lshl_b64 s[18:19], s[14:15], 19
	s_add_u32 s18, s26, s18
	s_addc_u32 s19, s27, s19
	s_and_b64 s[20:21], s[20:21], exec
	s_cselect_b32 s15, s19, s3
	s_cselect_b32 s40, s18, s2
	s_add_u32 s41, s2, 0x100
	v_mov_b32_e32 v2, 0
	s_addc_u32 s42, s3, 0
	s_mov_b32 s43, -2
	v_mov_b32_e32 v3, v2
	v_mov_b32_e32 v4, v2
	v_mov_b32_e32 v5, v2
	v_mov_b32_e32 v6, v2
	v_mov_b32_e32 v7, v2
	v_mov_b32_e32 v8, v2
	v_mov_b32_e32 v9, v2
	v_mov_b32_e32 v18, v2
	v_mov_b32_e32 v19, v2
	v_mov_b32_e32 v20, v2
	v_mov_b32_e32 v21, v2
	v_mov_b32_e32 v22, v2
	v_mov_b32_e32 v23, v2
	v_mov_b32_e32 v24, v2
	v_mov_b32_e32 v25, v2
	v_mov_b32_e32 v34, v2
	v_mov_b32_e32 v35, v2
	v_mov_b32_e32 v36, v2
	v_mov_b32_e32 v37, v2
	v_mov_b32_e32 v38, v2
	v_mov_b32_e32 v39, v2
	v_mov_b32_e32 v40, v2
	v_mov_b32_e32 v41, v2
	v_mov_b32_e32 v50, v2
	v_mov_b32_e32 v51, v2
	v_mov_b32_e32 v52, v2
	v_mov_b32_e32 v53, v2
	v_mov_b32_e32 v54, v2
	v_mov_b32_e32 v55, v2
	v_mov_b32_e32 v56, v2
	v_mov_b32_e32 v57, v2
	v_mov_b32_e32 v10, v2
	v_mov_b32_e32 v11, v2
	v_mov_b32_e32 v12, v2
	v_mov_b32_e32 v13, v2
	v_mov_b32_e32 v14, v2
	v_mov_b32_e32 v15, v2
	v_mov_b32_e32 v16, v2
	v_mov_b32_e32 v17, v2
	v_mov_b32_e32 v26, v2
	v_mov_b32_e32 v27, v2
	v_mov_b32_e32 v28, v2
	v_mov_b32_e32 v29, v2
	v_mov_b32_e32 v30, v2
	v_mov_b32_e32 v31, v2
	v_mov_b32_e32 v32, v2
	v_mov_b32_e32 v33, v2
	v_mov_b32_e32 v42, v2
	v_mov_b32_e32 v43, v2
	v_mov_b32_e32 v44, v2
	v_mov_b32_e32 v45, v2
	v_mov_b32_e32 v46, v2
	v_mov_b32_e32 v47, v2
	v_mov_b32_e32 v48, v2
	v_mov_b32_e32 v49, v2
	v_mov_b32_e32 v58, v2
	v_mov_b32_e32 v59, v2
	v_mov_b32_e32 v60, v2
	v_mov_b32_e32 v61, v2
	v_mov_b32_e32 v62, v2
	v_mov_b32_e32 v63, v2
	v_mov_b32_e32 v64, v2
	v_mov_b32_e32 v65, v2
	v_mov_b32_e32 v66, v2
	v_mov_b32_e32 v67, v2
	v_mov_b32_e32 v68, v2
	v_mov_b32_e32 v69, v2
	v_mov_b32_e32 v70, v2
	v_mov_b32_e32 v71, v2
	v_mov_b32_e32 v72, v2
	v_mov_b32_e32 v73, v2
	v_mov_b32_e32 v82, v2
	v_mov_b32_e32 v83, v2
	v_mov_b32_e32 v84, v2
	v_mov_b32_e32 v85, v2
	v_mov_b32_e32 v86, v2
	v_mov_b32_e32 v87, v2
	v_mov_b32_e32 v88, v2
	v_mov_b32_e32 v89, v2
	v_mov_b32_e32 v98, v2
	v_mov_b32_e32 v99, v2
	v_mov_b32_e32 v100, v2
	v_mov_b32_e32 v101, v2
	v_mov_b32_e32 v102, v2
	v_mov_b32_e32 v103, v2
	v_mov_b32_e32 v104, v2
	v_mov_b32_e32 v105, v2
	v_mov_b32_e32 v114, v2
	v_mov_b32_e32 v115, v2
	v_mov_b32_e32 v116, v2
	v_mov_b32_e32 v117, v2
	v_mov_b32_e32 v118, v2
	v_mov_b32_e32 v119, v2
	v_mov_b32_e32 v120, v2
	v_mov_b32_e32 v121, v2
	v_mov_b32_e32 v74, v2
	v_mov_b32_e32 v75, v2
	v_mov_b32_e32 v76, v2
	v_mov_b32_e32 v77, v2
	v_mov_b32_e32 v78, v2
	v_mov_b32_e32 v79, v2
	v_mov_b32_e32 v80, v2
	v_mov_b32_e32 v81, v2
	v_mov_b32_e32 v90, v2
	v_mov_b32_e32 v91, v2
	v_mov_b32_e32 v92, v2
	v_mov_b32_e32 v93, v2
	v_mov_b32_e32 v94, v2
	v_mov_b32_e32 v95, v2
	v_mov_b32_e32 v96, v2
	v_mov_b32_e32 v97, v2
	v_mov_b32_e32 v106, v2
	v_mov_b32_e32 v107, v2
	v_mov_b32_e32 v108, v2
	v_mov_b32_e32 v109, v2
	v_mov_b32_e32 v110, v2
	v_mov_b32_e32 v111, v2
	v_mov_b32_e32 v112, v2
	v_mov_b32_e32 v113, v2
	v_mov_b32_e32 v122, v2
	v_mov_b32_e32 v123, v2
	v_mov_b32_e32 v124, v2
	v_mov_b32_e32 v125, v2
	v_mov_b32_e32 v126, v2
	v_mov_b32_e32 v127, v2
	v_mov_b32_e32 v128, v2
	v_mov_b32_e32 v129, v2
	.p2align 6

; template <class Epi, bool ALIGN_EPI>
; __device__ __forceinline__ void gemm_phase(LAS unsigned char* lds, const Gemm g, const StaticOrder& S, const Epi& E) {
;     ...
;         const bool has_next = S.next(ui + 1, nxt);
;         const char* nA = has_next ? (const char*)g.A + (size_t)nxt.pm * tstepA : cA; const char* nB = has_next ? (const char*)g.Bt + (size_t)nxt.pn * tstepB : cB;
;     ...
; #pragma unroll
;         for (int a = 0; a < 2; ++a)
; #pragma unroll
;             for (int b = 0; b < 2; ++b)
; #pragma unroll
;                 for (int m = 0; m < 4; ++m)
; #pragma unroll
;                     for (int n = 0; n < 2; ++n) acc[a][b][m][n] = (f32x4){0.f, 0.f, 0.f, 0.f};
.LBB0_482:
	s_ashr_i32 s1, s0, 31
	s_lshl_b64 s[14:15], s[0:1], 19
	v_readlane_b32 s16, v254, 45
	v_readlane_b32 s17, v254, 46
	s_add_u32 s14, s16, s14
	s_addc_u32 s15, s17, s15
	s_and_b64 s[16:17], s[12:13], exec
	s_cselect_b32 s1, s15, s7
	s_cselect_b32 s36, s14, s6
	s_ashr_i32 s11, s10, 31
	s_lshl_b64 s[16:17], s[10:11], 19
	s_add_u32 s16, s22, s16
	s_addc_u32 s17, s23, s17
	s_and_b64 s[20:21], s[12:13], exec
	s_cselect_b32 s11, s17, s19
	s_cselect_b32 s37, s16, s18
	s_add_u32 s6, s6, 0x40080
	s_addc_u32 s7, s7, 0
	s_add_u32 s38, s18, 0x100
	v_mov_b32_e32 v2, 0
	s_addc_u32 s39, s19, 0
	s_mov_b32 s40, -2
	v_mov_b32_e32 v3, v2
	v_mov_b32_e32 v4, v2
	v_mov_b32_e32 v5, v2
	v_mov_b32_e32 v6, v2
	v_mov_b32_e32 v7, v2
	v_mov_b32_e32 v8, v2
	v_mov_b32_e32 v9, v2
	v_mov_b32_e32 v18, v2
	v_mov_b32_e32 v19, v2
	v_mov_b32_e32 v20, v2
	v_mov_b32_e32 v21, v2
	v_mov_b32_e32 v22, v2
	v_mov_b32_e32 v23, v2
	v_mov_b32_e32 v24, v2
	v_mov_b32_e32 v25, v2
	v_mov_b32_e32 v34, v2
	v_mov_b32_e32 v35, v2
	v_mov_b32_e32 v36, v2
	v_mov_b32_e32 v37, v2
	v_mov_b32_e32 v38, v2
	v_mov_b32_e32 v39, v2
	v_mov_b32_e32 v40, v2
	v_mov_b32_e32 v41, v2
	v_mov_b32_e32 v50, v2
	v_mov_b32_e32 v51, v2
	v_mov_b32_e32 v52, v2
	v_mov_b32_e32 v53, v2
	v_mov_b32_e32 v54, v2
	v_mov_b32_e32 v55, v2
	v_mov_b32_e32 v56, v2
	v_mov_b32_e32 v57, v2
	v_mov_b32_e32 v10, v2
	v_mov_b32_e32 v11, v2
	v_mov_b32_e32 v12, v2
	v_mov_b32_e32 v13, v2
	v_mov_b32_e32 v14, v2
	v_mov_b32_e32 v15, v2
	v_mov_b32_e32 v16, v2
	v_mov_b32_e32 v17, v2
	v_mov_b32_e32 v26, v2
	v_mov_b32_e32 v27, v2
	v_mov_b32_e32 v28, v2
	v_mov_b32_e32 v29, v2
	v_mov_b32_e32 v30, v2
	v_mov_b32_e32 v31, v2
	v_mov_b32_e32 v32, v2
	v_mov_b32_e32 v33, v2
	v_mov_b32_e32 v42, v2
	v_mov_b32_e32 v43, v2
	v_mov_b32_e32 v44, v2
	v_mov_b32_e32 v45, v2
	v_mov_b32_e32 v46, v2
	v_mov_b32_e32 v47, v2
	v_mov_b32_e32 v48, v2
	v_mov_b32_e32 v49, v2
	v_mov_b32_e32 v58, v2
	v_mov_b32_e32 v59, v2
	v_mov_b32_e32 v60, v2
	v_mov_b32_e32 v61, v2
	v_mov_b32_e32 v62, v2
	v_mov_b32_e32 v63, v2
	v_mov_b32_e32 v64, v2
	v_mov_b32_e32 v65, v2
	v_mov_b32_e32 v66, v2
	v_mov_b32_e32 v67, v2
	v_mov_b32_e32 v68, v2
	v_mov_b32_e32 v69, v2
	v_mov_b32_e32 v70, v2
	v_mov_b32_e32 v71, v2
	v_mov_b32_e32 v72, v2
	v_mov_b32_e32 v73, v2
	v_mov_b32_e32 v82, v2
	v_mov_b32_e32 v83, v2
	v_mov_b32_e32 v84, v2
	v_mov_b32_e32 v85, v2
	v_mov_b32_e32 v86, v2
	v_mov_b32_e32 v87, v2
	v_mov_b32_e32 v88, v2
	v_mov_b32_e32 v89, v2
	v_mov_b32_e32 v98, v2
	v_mov_b32_e32 v99, v2
	v_mov_b32_e32 v100, v2
	v_mov_b32_e32 v101, v2
	v_mov_b32_e32 v102, v2
	v_mov_b32_e32 v103, v2
	v_mov_b32_e32 v104, v2
	v_mov_b32_e32 v105, v2
	v_mov_b32_e32 v114, v2
	v_mov_b32_e32 v115, v2
	v_mov_b32_e32 v116, v2
	v_mov_b32_e32 v117, v2
	v_mov_b32_e32 v118, v2
	v_mov_b32_e32 v119, v2
	v_mov_b32_e32 v120, v2
	v_mov_b32_e32 v121, v2
	v_mov_b32_e32 v74, v2
	v_mov_b32_e32 v75, v2
	v_mov_b32_e32 v76, v2
	v_mov_b32_e32 v77, v2
	v_mov_b32_e32 v78, v2
	v_mov_b32_e32 v79, v2
	v_mov_b32_e32 v80, v2
	v_mov_b32_e32 v81, v2
	v_mov_b32_e32 v90, v2
	v_mov_b32_e32 v91, v2
	v_mov_b32_e32 v92, v2
	v_mov_b32_e32 v93, v2
	v_mov_b32_e32 v94, v2
	v_mov_b32_e32 v95, v2
	v_mov_b32_e32 v96, v2
	v_mov_b32_e32 v97, v2
	v_mov_b32_e32 v106, v2
	v_mov_b32_e32 v107, v2
	v_mov_b32_e32 v108, v2
	v_mov_b32_e32 v109, v2
	v_mov_b32_e32 v110, v2
	v_mov_b32_e32 v111, v2
	v_mov_b32_e32 v112, v2
	v_mov_b32_e32 v113, v2
	v_mov_b32_e32 v122, v2
	v_mov_b32_e32 v123, v2
	v_mov_b32_e32 v124, v2
	v_mov_b32_e32 v125, v2
	v_mov_b32_e32 v126, v2
	v_mov_b32_e32 v127, v2
	v_mov_b32_e32 v128, v2
	v_mov_b32_e32 v129, v2
	.p2align 6

; template <class Epi, bool ALIGN_EPI>
; __device__ __forceinline__ void gemm_phase(LAS unsigned char* lds, const Gemm g, const StaticOrder& S, const Epi& E) {
;     ...
;         const bool has_next = S.next(ui + 1, nxt);
;         const char* nA = has_next ? (const char*)g.A + (size_t)nxt.pm * tstepA : cA; const char* nB = has_next ? (const char*)g.Bt + (size_t)nxt.pn * tstepB : cB;
;     ...
; #pragma unroll
;         for (int a = 0; a < 2; ++a)
; #pragma unroll
;             for (int b = 0; b < 2; ++b)
; #pragma unroll
;                 for (int m = 0; m < 4; ++m)
; #pragma unroll
;                     for (int n = 0; n < 2; ++n) acc[a][b][m][n] = (f32x4){0.f, 0.f, 0.f, 0.f};
.LBB0_602:
	s_ashr_i32 s9, s8, 31
	s_lshl_b64 s[18:19], s[8:9], 19
	v_readlane_b32 s20, v254, 45
	v_readlane_b32 s21, v254, 46
	s_add_u32 s18, s20, s18
	s_addc_u32 s19, s21, s19
	s_and_b64 s[20:21], s[16:17], exec
	s_cselect_b32 s9, s19, s7
	s_cselect_b32 s40, s18, s6
	s_ashr_i32 s15, s14, 31
	s_lshl_b64 s[20:21], s[14:15], 19
	s_add_u32 s20, s4, s20
	s_addc_u32 s21, s28, s21
	s_and_b64 s[26:27], s[16:17], exec
	s_cselect_b32 s15, s21, s25
	s_cselect_b32 s41, s20, s24
	s_add_u32 s6, s6, 0x40080
	s_addc_u32 s7, s7, 0
	s_add_u32 s42, s24, 0x100
	v_mov_b32_e32 v62, 0
	s_addc_u32 s43, s25, 0
	s_mov_b32 s44, -2
	v_mov_b32_e32 v63, v62
	v_mov_b32_e32 v64, v62
	v_mov_b32_e32 v65, v62
	v_mov_b32_e32 v70, v62
	v_mov_b32_e32 v71, v62
	v_mov_b32_e32 v72, v62
	v_mov_b32_e32 v73, v62
	v_mov_b32_e32 v74, v62
	v_mov_b32_e32 v75, v62
	v_mov_b32_e32 v76, v62
	v_mov_b32_e32 v77, v62
	v_mov_b32_e32 v78, v62
	v_mov_b32_e32 v79, v62
	v_mov_b32_e32 v80, v62
	v_mov_b32_e32 v81, v62
	v_mov_b32_e32 v82, v62
	v_mov_b32_e32 v83, v62
	v_mov_b32_e32 v84, v62
	v_mov_b32_e32 v85, v62
	v_mov_b32_e32 v86, v62
	v_mov_b32_e32 v87, v62
	v_mov_b32_e32 v88, v62
	v_mov_b32_e32 v89, v62
	v_mov_b32_e32 v90, v62
	v_mov_b32_e32 v91, v62
	v_mov_b32_e32 v92, v62
	v_mov_b32_e32 v93, v62
	v_mov_b32_e32 v94, v62
	v_mov_b32_e32 v95, v62
	v_mov_b32_e32 v96, v62
	v_mov_b32_e32 v97, v62
	v_mov_b32_e32 v2, v62
	v_mov_b32_e32 v3, v62
	v_mov_b32_e32 v4, v62
	v_mov_b32_e32 v5, v62
	v_mov_b32_e32 v6, v62
	v_mov_b32_e32 v7, v62
	v_mov_b32_e32 v8, v62
	v_mov_b32_e32 v9, v62
	v_mov_b32_e32 v10, v62
	v_mov_b32_e32 v11, v62
	v_mov_b32_e32 v12, v62
	v_mov_b32_e32 v13, v62
	v_mov_b32_e32 v14, v62
	v_mov_b32_e32 v15, v62
	v_mov_b32_e32 v16, v62
	v_mov_b32_e32 v17, v62
	v_mov_b32_e32 v18, v62
	v_mov_b32_e32 v19, v62
	v_mov_b32_e32 v20, v62
	v_mov_b32_e32 v21, v62
	v_mov_b32_e32 v22, v62
	v_mov_b32_e32 v23, v62
	v_mov_b32_e32 v24, v62
	v_mov_b32_e32 v25, v62
	v_mov_b32_e32 v26, v62
	v_mov_b32_e32 v27, v62
	v_mov_b32_e32 v28, v62
	v_mov_b32_e32 v29, v62
	v_mov_b32_e32 v30, v62
	v_mov_b32_e32 v31, v62
	v_mov_b32_e32 v32, v62
	v_mov_b32_e32 v33, v62
	v_mov_b32_e32 v98, v62
	v_mov_b32_e32 v99, v62
	v_mov_b32_e32 v100, v62
	v_mov_b32_e32 v101, v62
	v_mov_b32_e32 v102, v62
	v_mov_b32_e32 v103, v62
	v_mov_b32_e32 v104, v62
	v_mov_b32_e32 v105, v62
	v_mov_b32_e32 v106, v62
	v_mov_b32_e32 v107, v62
	v_mov_b32_e32 v108, v62
	v_mov_b32_e32 v109, v62
	v_mov_b32_e32 v110, v62
	v_mov_b32_e32 v111, v62
	v_mov_b32_e32 v112, v62
	v_mov_b32_e32 v113, v62
	v_mov_b32_e32 v114, v62
	v_mov_b32_e32 v115, v62
	v_mov_b32_e32 v116, v62
	v_mov_b32_e32 v117, v62
	v_mov_b32_e32 v118, v62
	v_mov_b32_e32 v119, v62
	v_mov_b32_e32 v120, v62
	v_mov_b32_e32 v121, v62
	v_mov_b32_e32 v122, v62
	v_mov_b32_e32 v123, v62
	v_mov_b32_e32 v124, v62
	v_mov_b32_e32 v125, v62
	v_mov_b32_e32 v126, v62
	v_mov_b32_e32 v127, v62
	v_mov_b32_e32 v128, v62
	v_mov_b32_e32 v129, v62
	v_mov_b32_e32 v34, v62
	v_mov_b32_e32 v35, v62
	v_mov_b32_e32 v36, v62
	v_mov_b32_e32 v37, v62
	v_mov_b32_e32 v38, v62
	v_mov_b32_e32 v39, v62
	v_mov_b32_e32 v40, v62
	v_mov_b32_e32 v41, v62
	v_mov_b32_e32 v42, v62
	v_mov_b32_e32 v43, v62
	v_mov_b32_e32 v44, v62
	v_mov_b32_e32 v45, v62
	v_mov_b32_e32 v46, v62
	v_mov_b32_e32 v47, v62
	v_mov_b32_e32 v48, v62
	v_mov_b32_e32 v49, v62
	v_mov_b32_e32 v50, v62
	v_mov_b32_e32 v51, v62
	v_mov_b32_e32 v52, v62
	v_mov_b32_e32 v53, v62
	v_mov_b32_e32 v54, v62
	v_mov_b32_e32 v55, v62
	v_mov_b32_e32 v56, v62
	v_mov_b32_e32 v57, v62
	v_mov_b32_e32 v58, v62
	v_mov_b32_e32 v59, v62
	v_mov_b32_e32 v60, v62
	v_mov_b32_e32 v61, v62
	v_mov_b32_e32 v66, v62
	v_mov_b32_e32 v67, v62
	v_mov_b32_e32 v68, v62
	v_mov_b32_e32 v69, v62
	.p2align 6

; template <class Epi, bool ALIGN_EPI>
; __device__ __forceinline__ void gemm_phase(LAS unsigned char* lds, const Gemm g, const StaticOrder& S, const Epi& E) {
;     ...
;         for (int t = 0; t < nt; t += 2) {
;             const bool last = (t == nt - 2);
;             const char* a1 = cA + (size_t)(t + 1) * kstep;
;             const char* a2 = last ? nA : cA + (size_t)(t + 2) * kstep; const char* b2 = last ? nB : cB + (size_t)(t + 2) * kstep;
;             const char* a3 = a2 + kstep; const char* b3 = b2 + kstep;
;     ...
; #pragma unroll
;         for (int a = 0; a < 2; ++a)
; #pragma unroll
;             for (int b = 0; b < 2; ++b)
; #pragma unroll
;                 for (int m = 0; m < 4; ++m)
; #pragma unroll
;                     for (int n = 0; n < 2; ++n) acc[a][b][m][n] = (f32x4){0.f, 0.f, 0.f, 0.f};
.LBB0_718:
	s_add_u32 s29, s10, 0x100
	v_mov_b32_e32 v2, 0
	s_addc_u32 s44, s11, 0
	s_mov_b32 s45, -2
	s_waitcnt lgkmcnt(0)
	v_mov_b32_e32 v3, v2
	v_mov_b32_e32 v4, v2
	v_mov_b32_e32 v5, v2
	v_mov_b32_e32 v6, v2
	v_mov_b32_e32 v7, v2
	v_mov_b32_e32 v8, v2
	v_mov_b32_e32 v9, v2
	v_mov_b32_e32 v18, v2
	v_mov_b32_e32 v19, v2
	v_mov_b32_e32 v20, v2
	v_mov_b32_e32 v21, v2
	v_mov_b32_e32 v22, v2
	v_mov_b32_e32 v23, v2
	v_mov_b32_e32 v24, v2
	v_mov_b32_e32 v25, v2
	v_mov_b32_e32 v34, v2
	v_mov_b32_e32 v35, v2
	v_mov_b32_e32 v36, v2
	v_mov_b32_e32 v37, v2
	v_mov_b32_e32 v38, v2
	v_mov_b32_e32 v39, v2
	v_mov_b32_e32 v40, v2
	v_mov_b32_e32 v41, v2
	v_mov_b32_e32 v50, v2
	v_mov_b32_e32 v51, v2
	v_mov_b32_e32 v52, v2
	v_mov_b32_e32 v53, v2
	v_mov_b32_e32 v54, v2
	v_mov_b32_e32 v55, v2
	v_mov_b32_e32 v56, v2
	v_mov_b32_e32 v57, v2
	v_mov_b32_e32 v10, v2
	v_mov_b32_e32 v11, v2
	v_mov_b32_e32 v12, v2
	v_mov_b32_e32 v13, v2
	v_mov_b32_e32 v14, v2
	v_mov_b32_e32 v15, v2
	v_mov_b32_e32 v16, v2
	v_mov_b32_e32 v17, v2
	v_mov_b32_e32 v26, v2
	v_mov_b32_e32 v27, v2
	v_mov_b32_e32 v28, v2
	v_mov_b32_e32 v29, v2
	v_mov_b32_e32 v30, v2
	v_mov_b32_e32 v31, v2
	v_mov_b32_e32 v32, v2
	v_mov_b32_e32 v33, v2
	v_mov_b32_e32 v42, v2
	v_mov_b32_e32 v43, v2
	v_mov_b32_e32 v44, v2
	v_mov_b32_e32 v45, v2
	v_mov_b32_e32 v46, v2
	v_mov_b32_e32 v47, v2
	v_mov_b32_e32 v48, v2
	v_mov_b32_e32 v49, v2
	v_mov_b32_e32 v58, v2
	v_mov_b32_e32 v59, v2
	v_mov_b32_e32 v60, v2
	v_mov_b32_e32 v61, v2
	v_mov_b32_e32 v62, v2
	v_mov_b32_e32 v63, v2
	v_mov_b32_e32 v64, v2
	v_mov_b32_e32 v65, v2
	v_mov_b32_e32 v66, v2
	v_mov_b32_e32 v67, v2
	v_mov_b32_e32 v68, v2
	v_mov_b32_e32 v69, v2
	v_mov_b32_e32 v70, v2
	v_mov_b32_e32 v71, v2
	v_mov_b32_e32 v72, v2
	v_mov_b32_e32 v73, v2
	v_mov_b32_e32 v82, v2
	v_mov_b32_e32 v83, v2
	v_mov_b32_e32 v84, v2
	v_mov_b32_e32 v85, v2
	v_mov_b32_e32 v86, v2
	v_mov_b32_e32 v87, v2
	v_mov_b32_e32 v88, v2
	v_mov_b32_e32 v89, v2
	v_mov_b32_e32 v98, v2
	v_mov_b32_e32 v99, v2
	v_mov_b32_e32 v100, v2
	v_mov_b32_e32 v101, v2
	v_mov_b32_e32 v102, v2
	v_mov_b32_e32 v103, v2
	v_mov_b32_e32 v104, v2
	v_mov_b32_e32 v105, v2
	v_mov_b32_e32 v114, v2
	v_mov_b32_e32 v115, v2
	v_mov_b32_e32 v116, v2
	v_mov_b32_e32 v117, v2
	v_mov_b32_e32 v118, v2
	v_mov_b32_e32 v119, v2
	v_mov_b32_e32 v120, v2
	v_mov_b32_e32 v121, v2
	v_mov_b32_e32 v74, v2
	v_mov_b32_e32 v75, v2
	v_mov_b32_e32 v76, v2
	v_mov_b32_e32 v77, v2
	v_mov_b32_e32 v78, v2
	v_mov_b32_e32 v79, v2
	v_mov_b32_e32 v80, v2
	v_mov_b32_e32 v81, v2
	v_mov_b32_e32 v90, v2
	v_mov_b32_e32 v91, v2
	v_mov_b32_e32 v92, v2
	v_mov_b32_e32 v93, v2
	v_mov_b32_e32 v94, v2
	v_mov_b32_e32 v95, v2
	v_mov_b32_e32 v96, v2
	v_mov_b32_e32 v97, v2
	v_mov_b32_e32 v106, v2
	v_mov_b32_e32 v107, v2
	v_mov_b32_e32 v108, v2
	v_mov_b32_e32 v109, v2
	v_mov_b32_e32 v110, v2
	v_mov_b32_e32 v111, v2
	v_mov_b32_e32 v112, v2
	v_mov_b32_e32 v113, v2
	v_mov_b32_e32 v122, v2
	v_mov_b32_e32 v123, v2
	v_mov_b32_e32 v124, v2
	v_mov_b32_e32 v125, v2
	v_mov_b32_e32 v126, v2
	v_mov_b32_e32 v127, v2
	v_mov_b32_e32 v128, v2
	v_mov_b32_e32 v129, v2
	.p2align 6

; template <class Epi, bool ALIGN_EPI>
; __device__ __forceinline__ void gemm_phase(LAS unsigned char* lds, const Gemm g, const StaticOrder& S, const Epi& E) {
;     ...
;         const bool has_next = S.next(ui + 1, nxt);
;         const char* nA = has_next ? (const char*)g.A + (size_t)nxt.pm * tstepA : cA; const char* nB = has_next ? (const char*)g.Bt + (size_t)nxt.pn * tstepB : cB;
;     ...
; #pragma unroll
;         for (int a = 0; a < 2; ++a)
; #pragma unroll
;             for (int b = 0; b < 2; ++b)
; #pragma unroll
;                 for (int m = 0; m < 4; ++m)
; #pragma unroll
;                     for (int n = 0; n < 2; ++n) acc[a][b][m][n] = (f32x4){0.f, 0.f, 0.f, 0.f};
.LBB0_848:
	s_ashr_i32 s1, s0, 31
	s_lshl_b64 s[14:15], s[0:1], 19
	v_readlane_b32 s16, v254, 47
	v_readlane_b32 s17, v254, 48
	s_add_u32 s14, s16, s14
	s_addc_u32 s15, s17, s15
	s_and_b64 s[16:17], s[12:13], exec
	s_cselect_b32 s1, s15, s7
	s_cselect_b32 s34, s14, s6
	s_ashr_i32 s11, s10, 31
	s_lshl_b64 s[16:17], s[10:11], 19
	s_add_u32 s16, s78, s16
	s_addc_u32 s17, s79, s17
	s_and_b64 s[20:21], s[12:13], exec
	s_cselect_b32 s11, s17, s19
	s_cselect_b32 s35, s16, s18
	s_add_u32 s6, s6, 0x40080
	s_addc_u32 s7, s7, 0
	s_add_u32 s36, s18, 0x100
	v_mov_b32_e32 v2, 0
	s_addc_u32 s37, s19, 0
	s_mov_b32 s38, -2
	v_mov_b32_e32 v3, v2
	v_mov_b32_e32 v4, v2
	v_mov_b32_e32 v5, v2
	v_mov_b32_e32 v10, v2
	v_mov_b32_e32 v11, v2
	v_mov_b32_e32 v12, v2
	v_mov_b32_e32 v13, v2
	v_mov_b32_e32 v18, v2
	v_mov_b32_e32 v19, v2
	v_mov_b32_e32 v20, v2
	v_mov_b32_e32 v21, v2
	v_mov_b32_e32 v26, v2
	v_mov_b32_e32 v27, v2
	v_mov_b32_e32 v28, v2
	v_mov_b32_e32 v29, v2
	v_mov_b32_e32 v34, v2
	v_mov_b32_e32 v35, v2
	v_mov_b32_e32 v36, v2
	v_mov_b32_e32 v37, v2
	v_mov_b32_e32 v42, v2
	v_mov_b32_e32 v43, v2
	v_mov_b32_e32 v44, v2
	v_mov_b32_e32 v45, v2
	v_mov_b32_e32 v50, v2
	v_mov_b32_e32 v51, v2
	v_mov_b32_e32 v52, v2
	v_mov_b32_e32 v53, v2
	v_mov_b32_e32 v58, v2
	v_mov_b32_e32 v59, v2
	v_mov_b32_e32 v60, v2
	v_mov_b32_e32 v61, v2
	v_mov_b32_e32 v6, v2
	v_mov_b32_e32 v7, v2
	v_mov_b32_e32 v8, v2
	v_mov_b32_e32 v9, v2
	v_mov_b32_e32 v14, v2
	v_mov_b32_e32 v15, v2
	v_mov_b32_e32 v16, v2
	v_mov_b32_e32 v17, v2
	v_mov_b32_e32 v22, v2
	v_mov_b32_e32 v23, v2
	v_mov_b32_e32 v24, v2
	v_mov_b32_e32 v25, v2
	v_mov_b32_e32 v30, v2
	v_mov_b32_e32 v31, v2
	v_mov_b32_e32 v32, v2
	v_mov_b32_e32 v33, v2
	v_mov_b32_e32 v38, v2
	v_mov_b32_e32 v39, v2
	v_mov_b32_e32 v40, v2
	v_mov_b32_e32 v41, v2
	v_mov_b32_e32 v46, v2
	v_mov_b32_e32 v47, v2
	v_mov_b32_e32 v48, v2
	v_mov_b32_e32 v49, v2
	v_mov_b32_e32 v54, v2
	v_mov_b32_e32 v55, v2
	v_mov_b32_e32 v56, v2
	v_mov_b32_e32 v57, v2
	v_mov_b32_e32 v62, v2
	v_mov_b32_e32 v63, v2
	v_mov_b32_e32 v64, v2
	v_mov_b32_e32 v65, v2
	v_mov_b32_e32 v66, v2
	v_mov_b32_e32 v67, v2
	v_mov_b32_e32 v68, v2
	v_mov_b32_e32 v69, v2
	v_mov_b32_e32 v74, v2
	v_mov_b32_e32 v75, v2
	v_mov_b32_e32 v76, v2
	v_mov_b32_e32 v77, v2
	v_mov_b32_e32 v82, v2
	v_mov_b32_e32 v83, v2
	v_mov_b32_e32 v84, v2
	v_mov_b32_e32 v85, v2
	v_mov_b32_e32 v90, v2
	v_mov_b32_e32 v91, v2
	v_mov_b32_e32 v92, v2
	v_mov_b32_e32 v93, v2
	v_mov_b32_e32 v98, v2
	v_mov_b32_e32 v99, v2
	v_mov_b32_e32 v100, v2
	v_mov_b32_e32 v101, v2
	v_mov_b32_e32 v106, v2
	v_mov_b32_e32 v107, v2
	v_mov_b32_e32 v108, v2
	v_mov_b32_e32 v109, v2
	v_mov_b32_e32 v114, v2
	v_mov_b32_e32 v115, v2
	v_mov_b32_e32 v116, v2
	v_mov_b32_e32 v117, v2
	v_mov_b32_e32 v122, v2
	v_mov_b32_e32 v123, v2
	v_mov_b32_e32 v124, v2
	v_mov_b32_e32 v125, v2
	v_mov_b32_e32 v70, v2
	v_mov_b32_e32 v71, v2
	v_mov_b32_e32 v72, v2
	v_mov_b32_e32 v73, v2
	v_mov_b32_e32 v78, v2
	v_mov_b32_e32 v79, v2
	v_mov_b32_e32 v80, v2
	v_mov_b32_e32 v81, v2
	v_mov_b32_e32 v86, v2
	v_mov_b32_e32 v87, v2
	v_mov_b32_e32 v88, v2
	v_mov_b32_e32 v89, v2
	v_mov_b32_e32 v94, v2
	v_mov_b32_e32 v95, v2
	v_mov_b32_e32 v96, v2
	v_mov_b32_e32 v97, v2
	v_mov_b32_e32 v102, v2
	v_mov_b32_e32 v103, v2
	v_mov_b32_e32 v104, v2
	v_mov_b32_e32 v105, v2
	v_mov_b32_e32 v110, v2
	v_mov_b32_e32 v111, v2
	v_mov_b32_e32 v112, v2
	v_mov_b32_e32 v113, v2
	v_mov_b32_e32 v118, v2
	v_mov_b32_e32 v119, v2
	v_mov_b32_e32 v120, v2
	v_mov_b32_e32 v121, v2
	v_mov_b32_e32 v126, v2
	v_mov_b32_e32 v127, v2
	v_mov_b32_e32 v128, v2
	v_mov_b32_e32 v129, v2
	.p2align 6
